# gla_finalize: head-norm gains loaded once per iteration and reused from registers, so units 1-3 no longer wait for the previous unit's store to complete
# speedup vs baseline: 1.0137x; 1.0137x over previous
; __device__ __forceinline__ unsigned pk2(float lo, float hi) { f32x2 v = {lo, hi}; bf16x2_t b = __builtin_convertvector(v, bf16x2_t); return __builtin_bit_cast(unsigned, b); }
; __device__ __forceinline__ float silu_(float x) { return x * sigm(x); }
; __device__ __forceinline__ void unpack8(const u32x4 w, float (&f)[8]) { f[0] = bflo(w.x); f[1] = bfhi(w.x); f[2] = bflo(w.y); f[3] = bfhi(w.y); f[4] = bflo(w.z); f[5] = bfhi(w.z); f[6] = bflo(w.w); f[7] = bfhi(w.w); }
; __device__ __forceinline__ void gla_finalize(const Ctx& P, int l) {
;     ...
;     for (int it0 = gt; it0 < MP * 128; it0 += 4 * NT) {
;         u32x4 ovw[4], gvw[4]; float rs[4];
; #pragma unroll
;         for (int u = 0; u < 4; ++u) { const int it = it0 + u * NT; if (it < MP * 128) { const int row = it >> 7, c8 = (it & 127) * 8, h = c8 >> 8;
;             ovw[u] = *(const u32x4*)(OG + (size_t)row * D + c8); gvw[u] = *(const u32x4*)(Z + (size_t)row * NZ + ZC_GOUT + c8);
;             rs[u] = rsqrtf(ss_total(GSS + (size_t)h * 16, row * 4) * (1.f / 256.f) + EPS); } }
; #pragma unroll
;         for (int u = 0; u < 4; ++u) { const int it = it0 + u * NT; if (it < MP * 128) { const int row = it >> 7, c8 = (it & 127) * 8;
;             float ov[8], gv[8], gn[8]; unpack8(ovw[u], ov); unpack8(gvw[u], gv); load8f(p_gn + c8, gn);
; #pragma unroll
;             for (int i = 0; i < 8; ++i) ov[i] = ov[i] * rs[u] * gn[i] * silu_(gv[i]);
;             u32x4 o; o.x = pk2(ov[0], ov[1]); o.y = pk2(ov[2], ov[3]); o.z = pk2(ov[4], ov[5]); o.w = pk2(ov[6], ov[7]);
;             *(u32x4*)(OG + (size_t)row * D + c8) = o; } }
.LBB0_683:
	s_or_b64 exec, exec, s[10:11]
	v_lshlrev_b32_e32 v0, 2, v40
	v_lshl_add_u64 v[44:45], s[4:5], 0, v[0:1]
	flat_load_dwordx4 v[54:57], v[44:45]
	flat_load_dwordx4 v[38:41], v[44:45] offset:16
	v_lshlrev_b32_e32 v58, 16, v30
	v_mul_f32_e32 v0, 0xbfb8aa3b, v58
	v_exp_f32_e32 v0, v0
	v_and_b32_e32 v59, 0xffff0000, v30
	v_lshlrev_b32_e32 v30, 16, v31
	v_lshlrev_b32_e32 v48, 16, v34
	v_add_f32_e32 v0, 1.0, v0
	v_rcp_f32_e32 v60, v0
	v_mul_f32_e32 v0, 0xbfb8aa3b, v59
	v_exp_f32_e32 v0, v0
	v_and_b32_e32 v49, 0xffff0000, v34
	v_pk_mul_f32 v[48:49], v[2:3], v[48:49] op_sel_hi:[0,1]
	v_and_b32_e32 v31, 0xffff0000, v31
	v_add_f32_e32 v0, 1.0, v0
	v_rcp_f32_e32 v61, v0
	v_mul_f32_e32 v0, 0xbfb8aa3b, v30
	v_exp_f32_e32 v0, v0
	v_lshlrev_b32_e32 v34, 16, v35
	v_and_b32_e32 v35, 0xffff0000, v35
	v_pk_mul_f32 v[34:35], v[2:3], v[34:35] op_sel_hi:[0,1]
	v_add_f32_e32 v0, 1.0, v0
	s_waitcnt vmcnt(0) lgkmcnt(0)
	v_mov_b32_e32 v100, v54
	v_mov_b32_e32 v101, v55
	v_mov_b32_e32 v102, v56
	v_mov_b32_e32 v103, v57
	v_mov_b32_e32 v104, v38
	v_mov_b32_e32 v105, v39
	v_mov_b32_e32 v106, v40
	v_mov_b32_e32 v107, v41
	v_pk_mul_f32 v[48:49], v[54:55], v[48:49]
	v_pk_mul_f32 v[54:55], v[60:61], v[58:59]
	v_pk_mul_f32 v[34:35], v[56:57], v[34:35]
	v_pk_mul_f32 v[48:49], v[54:55], v[48:49]
	v_rcp_f32_e32 v54, v0
	v_mul_f32_e32 v0, 0xbfb8aa3b, v31
	v_exp_f32_e32 v0, v0
	s_nop 0
	v_add_f32_e32 v0, 1.0, v0
	v_rcp_f32_e32 v55, v0
	s_nop 0
	v_pk_mul_f32 v[30:31], v[54:55], v[30:31]
	v_lshlrev_b32_e32 v54, 16, v32
	v_mul_f32_e32 v0, 0xbfb8aa3b, v54
	v_exp_f32_e32 v0, v0
	v_and_b32_e32 v55, 0xffff0000, v32
	v_lshlrev_b32_e32 v32, 16, v33
	v_pk_mul_f32 v[30:31], v[30:31], v[34:35]
	v_add_f32_e32 v0, 1.0, v0
	v_rcp_f32_e32 v56, v0
	v_mul_f32_e32 v0, 0xbfb8aa3b, v55
	v_exp_f32_e32 v0, v0
	v_lshlrev_b32_e32 v34, 16, v36
	v_and_b32_e32 v35, 0xffff0000, v36
	v_pk_mul_f32 v[34:35], v[2:3], v[34:35] op_sel_hi:[0,1]
	v_add_f32_e32 v0, 1.0, v0
	v_rcp_f32_e32 v57, v0
	v_mul_f32_e32 v0, 0xbfb8aa3b, v32
	v_exp_f32_e32 v0, v0
	v_pk_mul_f32 v[34:35], v[34:35], v[38:39]
	v_pk_mul_f32 v[38:39], v[56:57], v[54:55]
	v_and_b32_e32 v33, 0xffff0000, v33
	v_add_f32_e32 v0, 1.0, v0
	v_pk_mul_f32 v[34:35], v[38:39], v[34:35]
	v_rcp_f32_e32 v38, v0
	v_mul_f32_e32 v0, 0xbfb8aa3b, v33
	v_exp_f32_e32 v0, v0
	v_lshlrev_b32_e32 v36, 16, v37
	v_and_b32_e32 v37, 0xffff0000, v37
	v_pk_mul_f32 v[36:37], v[2:3], v[36:37] op_sel_hi:[0,1]
	v_add_f32_e32 v0, 1.0, v0
	v_rcp_f32_e32 v39, v0
	v_pk_mul_f32 v[36:37], v[36:37], v[40:41]
	v_cvt_pk_bf16_f32 v34, v34, v35
	v_pk_mul_f32 v[32:33], v[38:39], v[32:33]
	s_nop 0
	v_pk_mul_f32 v[36:37], v[32:33], v[36:37]
	v_cvt_pk_bf16_f32 v32, v48, v49
	v_cvt_pk_bf16_f32 v33, v30, v31
	v_cvt_pk_bf16_f32 v35, v36, v37
	global_store_dwordx4 v[46:47], v[32:35], off
	s_and_saveexec_b64 s[10:11], s[42:43]
	s_cbranch_execnz .LBB0_686
	s_or_b64 exec, exec, s[10:11]
	s_and_saveexec_b64 s[10:11], s[40:41]
	s_cbranch_execnz .LBB0_687

; __device__ __forceinline__ unsigned pk2(float lo, float hi) { f32x2 v = {lo, hi}; bf16x2_t b = __builtin_convertvector(v, bf16x2_t); return __builtin_bit_cast(unsigned, b); }
; __device__ __forceinline__ float silu_(float x) { return x * sigm(x); }
; __device__ __forceinline__ void unpack8(const u32x4 w, float (&f)[8]) { f[0] = bflo(w.x); f[1] = bfhi(w.x); f[2] = bflo(w.y); f[3] = bfhi(w.y); f[4] = bflo(w.z); f[5] = bfhi(w.z); f[6] = bflo(w.w); f[7] = bfhi(w.w); }
; __device__ __forceinline__ void gla_finalize(const Ctx& P, int l) {
;     ...
;         for (int u = 0; u < 4; ++u) { const int it = it0 + u * NT; if (it < MP * 128) { const int row = it >> 7, c8 = (it & 127) * 8;
;             float ov[8], gv[8], gn[8]; unpack8(ovw[u], ov); unpack8(gvw[u], gv); load8f(p_gn + c8, gn);
; #pragma unroll
;             for (int i = 0; i < 8; ++i) ov[i] = ov[i] * rs[u] * gn[i] * silu_(gv[i]);
;             u32x4 o; o.x = pk2(ov[0], ov[1]); o.y = pk2(ov[2], ov[3]); o.z = pk2(ov[4], ov[5]); o.w = pk2(ov[6], ov[7]);
;             *(u32x4*)(OG + (size_t)row * D + c8) = o; } }
.LBB0_686:
	v_mov_b32_e32 v30, v100
	v_mov_b32_e32 v31, v101
	v_mov_b32_e32 v32, v102
	v_mov_b32_e32 v33, v103
	v_mov_b32_e32 v34, v104
	v_mov_b32_e32 v35, v105
	v_mov_b32_e32 v36, v106
	v_mov_b32_e32 v37, v107
	v_lshlrev_b32_e32 v40, 16, v18
	v_mul_f32_e32 v0, 0xbfb8aa3b, v40
	v_exp_f32_e32 v0, v0
	v_and_b32_e32 v41, 0xffff0000, v18
	v_lshlrev_b32_e32 v38, 16, v6
	v_and_b32_e32 v39, 0xffff0000, v6
	v_add_f32_e32 v0, 1.0, v0
	v_rcp_f32_e32 v46, v0
	v_mul_f32_e32 v0, 0xbfb8aa3b, v41
	v_exp_f32_e32 v0, v0
	v_pk_mul_f32 v[38:39], v[2:3], v[38:39] op_sel:[1,0]
	v_add_f32_e32 v0, 1.0, v0
	v_rcp_f32_e32 v47, v0
	s_waitcnt lgkmcnt(0)
	v_pk_mul_f32 v[30:31], v[38:39], v[30:31]
	v_pk_mul_f32 v[38:39], v[46:47], v[40:41]
	v_lshlrev_b32_e32 v40, 16, v19
	v_mul_f32_e32 v0, 0xbfb8aa3b, v40
	v_exp_f32_e32 v0, v0
	v_and_b32_e32 v41, 0xffff0000, v19
	v_pk_mul_f32 v[30:31], v[38:39], v[30:31]
	v_lshlrev_b32_e32 v38, 16, v7
	v_add_f32_e32 v0, 1.0, v0
	v_rcp_f32_e32 v46, v0
	v_mul_f32_e32 v0, 0xbfb8aa3b, v41
	v_exp_f32_e32 v0, v0
	v_and_b32_e32 v39, 0xffff0000, v7
	v_pk_mul_f32 v[38:39], v[2:3], v[38:39] op_sel:[1,0]
	v_cvt_pk_bf16_f32 v30, v30, v31
	v_add_f32_e32 v0, 1.0, v0
	v_rcp_f32_e32 v47, v0
	v_pk_mul_f32 v[32:33], v[38:39], v[32:33]
	v_pk_mul_f32 v[38:39], v[46:47], v[40:41]
	v_lshlrev_b32_e32 v40, 16, v20
	v_mul_f32_e32 v0, 0xbfb8aa3b, v40
	v_exp_f32_e32 v0, v0
	v_and_b32_e32 v41, 0xffff0000, v20
	v_pk_mul_f32 v[32:33], v[38:39], v[32:33]
	v_lshlrev_b32_e32 v38, 16, v8
	v_add_f32_e32 v0, 1.0, v0
	v_rcp_f32_e32 v46, v0
	v_mul_f32_e32 v0, 0xbfb8aa3b, v41
	v_exp_f32_e32 v0, v0
	v_and_b32_e32 v39, 0xffff0000, v8
	v_pk_mul_f32 v[38:39], v[2:3], v[38:39] op_sel:[1,0]
	v_cvt_pk_bf16_f32 v31, v32, v33
	v_add_f32_e32 v0, 1.0, v0
	v_rcp_f32_e32 v47, v0
	v_pk_mul_f32 v[34:35], v[38:39], v[34:35]
	v_pk_mul_f32 v[38:39], v[46:47], v[40:41]
	v_lshlrev_b32_e32 v40, 16, v21
	v_mul_f32_e32 v0, 0xbfb8aa3b, v40
	v_exp_f32_e32 v0, v0
	v_and_b32_e32 v41, 0xffff0000, v21
	v_pk_mul_f32 v[34:35], v[38:39], v[34:35]
	v_lshlrev_b32_e32 v38, 16, v9
	v_add_f32_e32 v0, 1.0, v0
	v_rcp_f32_e32 v46, v0
	v_mul_f32_e32 v0, 0xbfb8aa3b, v41
	v_exp_f32_e32 v0, v0
	v_and_b32_e32 v39, 0xffff0000, v9
	v_pk_mul_f32 v[38:39], v[2:3], v[38:39] op_sel:[1,0]
	v_cvt_pk_bf16_f32 v32, v34, v35
	v_add_f32_e32 v0, 1.0, v0
	v_rcp_f32_e32 v47, v0
	v_pk_mul_f32 v[36:37], v[38:39], v[36:37]
	v_pk_mul_f32 v[38:39], v[46:47], v[40:41]
	s_nop 0
	v_pk_mul_f32 v[36:37], v[38:39], v[36:37]
	v_ashrrev_i32_e32 v38, 7, v51
	v_ashrrev_i32_e32 v39, 31, v38
	v_lshlrev_b64 v[34:35], 11, v[38:39]
	v_cvt_pk_bf16_f32 v33, v36, v37
	v_lshl_add_u64 v[34:35], v[42:43], 0, v[34:35]
	global_store_dwordx4 v[34:35], v[30:33], off
	s_or_b64 exec, exec, s[10:11]
	s_and_saveexec_b64 s[10:11], s[40:41]
	s_cbranch_execz .LBB0_685
; __device__ __forceinline__ unsigned pk2(float lo, float hi) { f32x2 v = {lo, hi}; bf16x2_t b = __builtin_convertvector(v, bf16x2_t); return __builtin_bit_cast(unsigned, b); }
; __device__ __forceinline__ float silu_(float x) { return x * sigm(x); }
; __device__ __forceinline__ void unpack8(const u32x4 w, float (&f)[8]) { f[0] = bflo(w.x); f[1] = bfhi(w.x); f[2] = bflo(w.y); f[3] = bfhi(w.y); f[4] = bflo(w.z); f[5] = bfhi(w.z); f[6] = bflo(w.w); f[7] = bfhi(w.w); }
; __device__ __forceinline__ void gla_finalize(const Ctx& P, int l) {
;     ...
;         for (int u = 0; u < 4; ++u) { const int it = it0 + u * NT; if (it < MP * 128) { const int row = it >> 7, c8 = (it & 127) * 8;
;             float ov[8], gv[8], gn[8]; unpack8(ovw[u], ov); unpack8(gvw[u], gv); load8f(p_gn + c8, gn);
; #pragma unroll
;             for (int i = 0; i < 8; ++i) ov[i] = ov[i] * rs[u] * gn[i] * silu_(gv[i]);
;             u32x4 o; o.x = pk2(ov[0], ov[1]); o.y = pk2(ov[2], ov[3]); o.z = pk2(ov[4], ov[5]); o.w = pk2(ov[6], ov[7]);
;             *(u32x4*)(OG + (size_t)row * D + c8) = o; } }
.LBB0_687:
	v_mov_b32_e32 v30, v100
	v_mov_b32_e32 v31, v101
	v_mov_b32_e32 v32, v102
	v_mov_b32_e32 v33, v103
	v_mov_b32_e32 v34, v104
	v_mov_b32_e32 v35, v105
	v_mov_b32_e32 v36, v106
	v_mov_b32_e32 v37, v107
	v_lshlrev_b32_e32 v40, 16, v26
	v_mul_f32_e32 v0, 0xbfb8aa3b, v40
	v_exp_f32_e32 v0, v0
	v_and_b32_e32 v41, 0xffff0000, v26
	v_lshlrev_b32_e32 v38, 16, v14
	v_and_b32_e32 v39, 0xffff0000, v14
	v_add_f32_e32 v0, 1.0, v0
	v_rcp_f32_e32 v46, v0
	v_mul_f32_e32 v0, 0xbfb8aa3b, v41
	v_exp_f32_e32 v0, v0
	v_pk_mul_f32 v[38:39], v[4:5], v[38:39] op_sel_hi:[0,1]
	v_add_f32_e32 v0, 1.0, v0
	v_rcp_f32_e32 v47, v0
	s_waitcnt lgkmcnt(0)
	v_pk_mul_f32 v[30:31], v[38:39], v[30:31]
	v_pk_mul_f32 v[38:39], v[46:47], v[40:41]
	v_lshlrev_b32_e32 v40, 16, v27
	v_mul_f32_e32 v0, 0xbfb8aa3b, v40
	v_exp_f32_e32 v0, v0
	v_and_b32_e32 v41, 0xffff0000, v27
	v_pk_mul_f32 v[30:31], v[38:39], v[30:31]
	v_lshlrev_b32_e32 v38, 16, v15
	v_add_f32_e32 v0, 1.0, v0
	v_rcp_f32_e32 v46, v0
	v_mul_f32_e32 v0, 0xbfb8aa3b, v41
	v_exp_f32_e32 v0, v0
	v_and_b32_e32 v39, 0xffff0000, v15
	v_pk_mul_f32 v[38:39], v[4:5], v[38:39] op_sel_hi:[0,1]
	v_pk_mul_f32 v[32:33], v[38:39], v[32:33]
	v_add_f32_e32 v0, 1.0, v0
	v_rcp_f32_e32 v47, v0
	v_cvt_pk_bf16_f32 v30, v30, v31
	v_pk_mul_f32 v[38:39], v[46:47], v[40:41]
	v_lshlrev_b32_e32 v40, 16, v28
	v_mul_f32_e32 v0, 0xbfb8aa3b, v40
	v_exp_f32_e32 v0, v0
	v_and_b32_e32 v41, 0xffff0000, v28
	v_pk_mul_f32 v[32:33], v[38:39], v[32:33]
	v_lshlrev_b32_e32 v38, 16, v16
	v_add_f32_e32 v0, 1.0, v0
	v_rcp_f32_e32 v46, v0
	v_mul_f32_e32 v0, 0xbfb8aa3b, v41
	v_exp_f32_e32 v0, v0
	v_and_b32_e32 v39, 0xffff0000, v16
	v_pk_mul_f32 v[38:39], v[4:5], v[38:39] op_sel_hi:[0,1]
	v_pk_mul_f32 v[34:35], v[38:39], v[34:35]
	v_add_f32_e32 v0, 1.0, v0
	v_rcp_f32_e32 v47, v0
	v_cvt_pk_bf16_f32 v31, v32, v33
	v_pk_mul_f32 v[38:39], v[46:47], v[40:41]
	v_lshlrev_b32_e32 v40, 16, v29
	v_mul_f32_e32 v0, 0xbfb8aa3b, v40
	v_exp_f32_e32 v0, v0
	v_and_b32_e32 v41, 0xffff0000, v29
	v_pk_mul_f32 v[34:35], v[38:39], v[34:35]
	v_lshlrev_b32_e32 v38, 16, v17
	v_add_f32_e32 v0, 1.0, v0
	v_rcp_f32_e32 v46, v0
	v_mul_f32_e32 v0, 0xbfb8aa3b, v41
	v_exp_f32_e32 v0, v0
	v_and_b32_e32 v39, 0xffff0000, v17
	v_pk_mul_f32 v[38:39], v[4:5], v[38:39] op_sel_hi:[0,1]
	v_pk_mul_f32 v[36:37], v[38:39], v[36:37]
	v_add_f32_e32 v0, 1.0, v0
	v_rcp_f32_e32 v47, v0
	v_cvt_pk_bf16_f32 v32, v34, v35
	v_pk_mul_f32 v[38:39], v[46:47], v[40:41]
	s_nop 0
	v_pk_mul_f32 v[36:37], v[38:39], v[36:37]
	v_ashrrev_i32_e32 v38, 7, v53
	v_ashrrev_i32_e32 v39, 31, v38
	v_lshlrev_b64 v[34:35], 11, v[38:39]
	v_cvt_pk_bf16_f32 v33, v36, v37
	v_lshl_add_u64 v[34:35], v[42:43], 0, v[34:35]
	global_store_dwordx4 v[34:35], v[30:33], off
	s_or_b64 exec, exec, s[10:11]
	s_and_saveexec_b64 s[10:11], s[38:39]
	s_cbranch_execz .LBB0_676
.LBB0_688:
	v_mov_b32_e32 v30, v100
	v_mov_b32_e32 v31, v101
	v_mov_b32_e32 v32, v102
	v_mov_b32_e32 v33, v103
	v_mov_b32_e32 v34, v104
	v_mov_b32_e32 v35, v105
	v_mov_b32_e32 v36, v106
	v_mov_b32_e32 v37, v107
	v_lshlrev_b32_e32 v40, 16, v22
	v_and_b32_e32 v41, 0xffff0000, v22
	v_mul_f32_e32 v0, 0xbfb8aa3b, v40
	v_mul_f32_e32 v2, 0xbfb8aa3b, v41
	v_exp_f32_e32 v0, v0
	v_exp_f32_e32 v2, v2
	v_lshlrev_b32_e32 v38, 16, v10
	v_and_b32_e32 v39, 0xffff0000, v10
	v_add_f32_e32 v0, 1.0, v0
	v_add_f32_e32 v2, 1.0, v2
	v_rcp_f32_e32 v44, v0
	v_rcp_f32_e32 v45, v2
	v_mov_b32_e32 v0, v5
	v_pk_mul_f32 v[38:39], v[0:1], v[38:39] op_sel_hi:[0,1]
	s_waitcnt lgkmcnt(0)
	v_pk_mul_f32 v[30:31], v[38:39], v[30:31]
	v_pk_mul_f32 v[38:39], v[44:45], v[40:41]
	v_lshlrev_b32_e32 v40, 16, v23
	v_mul_f32_e32 v2, 0xbfb8aa3b, v40
	v_exp_f32_e32 v2, v2
	v_and_b32_e32 v41, 0xffff0000, v23
	v_pk_mul_f32 v[30:31], v[38:39], v[30:31]
	v_lshlrev_b32_e32 v38, 16, v11
	v_add_f32_e32 v2, 1.0, v2
	v_rcp_f32_e32 v44, v2
	v_mul_f32_e32 v2, 0xbfb8aa3b, v41
	v_exp_f32_e32 v2, v2
	v_and_b32_e32 v39, 0xffff0000, v11
	v_pk_mul_f32 v[38:39], v[0:1], v[38:39] op_sel_hi:[0,1]
	v_pk_mul_f32 v[32:33], v[38:39], v[32:33]
	v_add_f32_e32 v2, 1.0, v2
	v_rcp_f32_e32 v45, v2
	v_cvt_pk_bf16_f32 v30, v30, v31
	v_pk_mul_f32 v[38:39], v[44:45], v[40:41]
	v_lshlrev_b32_e32 v40, 16, v24
	v_mul_f32_e32 v2, 0xbfb8aa3b, v40
	v_exp_f32_e32 v2, v2
	v_and_b32_e32 v41, 0xffff0000, v24
	v_pk_mul_f32 v[32:33], v[38:39], v[32:33]
	v_lshlrev_b32_e32 v38, 16, v12
	v_add_f32_e32 v2, 1.0, v2
	v_rcp_f32_e32 v44, v2
	v_mul_f32_e32 v2, 0xbfb8aa3b, v41
	v_exp_f32_e32 v2, v2
	v_and_b32_e32 v39, 0xffff0000, v12
	v_pk_mul_f32 v[38:39], v[0:1], v[38:39] op_sel_hi:[0,1]
	v_pk_mul_f32 v[34:35], v[38:39], v[34:35]
	v_add_f32_e32 v2, 1.0, v2
	v_rcp_f32_e32 v45, v2
	v_cvt_pk_bf16_f32 v31, v32, v33
	v_pk_mul_f32 v[38:39], v[44:45], v[40:41]
	s_nop 0
	v_pk_mul_f32 v[34:35], v[38:39], v[34:35]
	v_lshlrev_b32_e32 v38, 16, v13
	v_and_b32_e32 v39, 0xffff0000, v13
	v_lshlrev_b32_e32 v40, 16, v25
	v_and_b32_e32 v41, 0xffff0000, v25
	v_mul_f32_e32 v2, 0xbfb8aa3b, v40
	v_pk_mul_f32 v[38:39], v[0:1], v[38:39] op_sel_hi:[0,1]
	v_mul_f32_e32 v0, 0xbfb8aa3b, v41
	v_exp_f32_e32 v2, v2
	v_exp_f32_e32 v0, v0
	v_pk_mul_f32 v[36:37], v[38:39], v[36:37]
	v_cvt_pk_bf16_f32 v32, v34, v35
	v_add_f32_e32 v2, 1.0, v2
	v_add_f32_e32 v0, 1.0, v0
	v_rcp_f32_e32 v44, v2
	v_rcp_f32_e32 v45, v0
	s_nop 0
	v_pk_mul_f32 v[38:39], v[44:45], v[40:41]
	s_nop 0
	v_pk_mul_f32 v[36:37], v[38:39], v[36:37]
	v_ashrrev_i32_e32 v38, 7, v52
	v_ashrrev_i32_e32 v39, 31, v38
	v_lshlrev_b64 v[34:35], 11, v[38:39]
	v_cvt_pk_bf16_f32 v33, v36, v37
	v_lshl_add_u64 v[34:35], v[42:43], 0, v[34:35]
	global_store_dwordx4 v[34:35], v[30:33], off
	s_branch .LBB0_676
